# v61 + layer-1 W_in transposes deferred to layer 0's mixer tail on workgroups >= 64; first queue fetch delayed 3us there so workgroups 0..63 take the prompt chains
# speedup vs baseline: 1.0249x; 1.0091x over previous
; #define GAS __attribute__((address_space(1)))
;     __device__ __forceinline__ int tid_() const { return wave * 64 + lane_id(); }
;     __device__ __forceinline__ GAS unsigned* ctl() const { return (GAS unsigned*)(wsp() + WS_CTL); }
; #define HG_BAR() do { asm volatile("s_waitcnt lgkmcnt(0)" ::: "memory"); __builtin_amdgcn_s_barrier(); asm volatile("" ::: "memory"); } while (0)
; __device__ __forceinline__ void phase_mixers(Frame& F, int layer, int qslot) {
;     GAS unsigned* head = F.ctl() + CW_QUEUE + 64 * qslot;
;     for (;;) {
;         if (F.tid_() == 0) F.MISC[4] = __hip_atomic_fetch_add(head, 1u, __ATOMIC_RELAXED, __HIP_MEMORY_SCOPE_AGENT);
;         HG_BAR();
.LBB0_559:
	s_cmp_lg_u32 s100, 0
	s_cbranch_scc1 .Ldv_q
	s_mov_b32 s100, 1
	s_cmpk_lt_u32 s101, 64
	s_cbranch_scc1 .Ldv_q
	s_sleep 100

;     __device__ __forceinline__ int lane_() const { return lane_id(); }
; #define F_w_in F.in(8)
; __device__ __forceinline__ void phase_prologue(Frame& F) {
;     ...
;     for (int it = gw; it < NITEMS; it += NGW) {
;         int r = it;
;         if (r < 2 * I_IN) { const int l = r / I_IN; p0_transpose_item(F_w_in + (size_t)l * D * NPROJ, D, NPROJ, win_t + (size_t)l * NPROJ * D, r % I_IN, F.lane_()); continue; } r -= 2 * I_IN;
;         if (r < 6 * I_SQ) { const int m = r / I_SQ; p0_transpose_item(F_w_branch + (size_t)m * D * D, D, D, wbr_t + (size_t)m * D * D, r % I_SQ, F.lane_()); continue; } r -= 6 * I_SQ;
;         if (r < 2 * I_SQ) { const int m = r / I_SQ; p0_transpose_item(F_w_out + (size_t)m * D * D, D, D, wout_t + (size_t)m * D * D, r % I_SQ, F.lane_()); continue; } r -= 2 * I_SQ;
;         { const int m = r / I_PL; p0_transpose_item(F_w_pool + (size_t)m * 65536, 256, 256, wpool_t + (size_t)m * 65536, r % I_PL, F.lane_()); }
;     }
.LBB0_881:
	v_readlane_b32 s8, v240, 7
	s_cmp_lg_u32 s8, 0
	s_cbranch_scc1 .Ldv_done
	s_cmpk_lt_u32 s101, 64
	s_cbranch_scc1 .Ldv_done
	v_mbcnt_lo_u32_b32 v182, -1, 0
	v_mbcnt_hi_u32_b32 v182, -1, v182
	v_mov_b32_e32 v188, 0x27d40
	v_mov_b32_e32 v190, s18
	ds_read_b64 v[188:189], v188
	ds_read_b64 v[190:191], v190
	v_lshrrev_b32_e32 v183, 4, v182
	v_and_b32_e32 v184, 15, v182
	v_mul_u32_u24_e32 v185, 0xd0000, v183
	v_lshl_add_u32 v185, v184, 4, v185
	v_lshlrev_b32_e32 v186, 13, v184
	v_lshl_add_u32 v186, v183, 5, v186
	v_add_u32_e32 v187, 0x1000, v186
	s_waitcnt lgkmcnt(0)
	v_readfirstlane_b32 s16, v188
	v_readfirstlane_b32 s17, v189
	v_readfirstlane_b32 s14, v190
	v_readfirstlane_b32 s15, v191
	s_add_u32 s16, s16, 0x3400000
	s_addc_u32 s17, s17, 0
	s_add_u32 s64, s14, 0x1c00000
	s_addc_u32 s65, s15, 0
	s_sub_u32 s61, s101, 64
	s_lshl_b32 s61, s61, 3
	s_lshr_b32 s8, s95, 10
	s_add_u32 s61, s61, s8
	s_branch .Ldv_first
.Ldv_next:
	s_addk_i32 s61, 0x600
